# leading half runs its epilogue at s_setprio 2 (finishes first, overlaps next unit's first load segment with the trailing half's epilogue)
# speedup vs baseline: 1.0042x; 1.0015x over previous
.Lzskip_0:
	s_and_b64 vcc, exec, s[76:77]
	s_cbranch_vccz .LBB0_123
	s_barrier
	s_setprio 2

.LBB0_130:
	s_setprio 0
	s_waitcnt vmcnt(0)
	s_barrier

.Lzskip_1:
	s_and_b64 vcc, exec, s[82:83]
	s_cbranch_vccz .LBB0_275
	s_barrier
	s_setprio 2

.LBB0_453:
	s_setprio 0
	s_waitcnt vmcnt(0)
	v_readlane_b32 s24, v254, 53
	v_readlane_b32 s26, v254, 55
	v_readlane_b32 s25, v254, 54
	v_readlane_b32 s27, v254, 56
	s_barrier

.Lzskip_3:
	s_and_b64 vcc, exec, s[48:49]
	s_cbranch_vccz .LBB0_996
	s_barrier
	s_setprio 2

.Lzskip_4:
	s_and_b64 vcc, exec, s[44:45]
	s_cbranch_vccz .LBB0_1151
	s_barrier
	s_setprio 2

.Lzskip_5:
	s_and_b64 vcc, exec, s[50:51]
	s_cbranch_vccz .LBB0_1302
	s_barrier
	s_setprio 2

.Lzskip_10:
	s_and_b64 vcc, exec, s[42:43]
	s_cbranch_vccz .LBB0_2195
	s_barrier
	s_setprio 2

.Lzskip_11:
	s_and_b64 vcc, exec, s[10:11]
	s_cbranch_vccz .LBB0_2344
	s_barrier
	s_setprio 2
